# KV-finalise row loop rewritten as a compact software-pipelined loop: next row's four loads requested before the current row is normalised/rotated/stored, invariant gain load hoisted
# baseline (speedup 1.0000x reference)
.Lmy_bsk14:
	s_ashr_i32 s7, s6, 31
	s_lshl_b64 s[6:7], s[6:7], 3
	v_readlane_b32 s8, v255, 2
	v_readlane_b32 s9, v255, 3
	s_add_u32 s6, s8, s6
	s_addc_u32 s7, s9, s7
	s_barrier
	s_load_dwordx2 s[6:7], s[6:7], 0x80
	v_and_b32_e32 v2, 63, v0
	v_mov_b32_e32 v9, v1
	v_lshlrev_b32_e32 v8, 4, v2
	v_mov_b32_e32 v3, 0x500
	s_waitcnt lgkmcnt(0)
	v_lshl_add_u64 v[4:5], s[6:7], 0, v[8:9]
	v_lshlrev_b32_e32 v12, 3, v2
	v_mov_b32_e32 v13, v1
	v_mad_i64_i32 v[8:9], s[12:13], s4, v3, v[8:9]
	v_lshlrev_b32_e32 v0, 2, v2
	v_mad_i64_i32 v[6:7], s[8:9], s4, v3, v[12:13]
	s_mov_b64 s[12:13], 0x264f7300
	v_mov_b32_e32 v3, 0x280
	v_lshl_add_u64 v[8:9], v[8:9], 0, s[12:13]
	v_mad_i64_i32 v[10:11], s[12:13], s4, v3, v[0:1]
	s_mov_b64 s[12:13], 0x27947500
	s_nop 0
	v_lshl_add_u64 v[10:11], v[10:11], 0, s[12:13]
	v_mad_i64_i32 v[12:13], s[12:13], s4, v3, v[12:13]
	s_lshl_b32 s6, s0, 3
	s_lshl_b32 s2, s84, 8
	s_lshl_b32 s1, s1, 5
	s_ashr_i32 s5, s4, 31
	s_mov_b64 s[12:13], 0x27947300
	s_add_i32 s1, s2, s1
	s_lshl_b32 s2, s0, 8
	s_ashr_i32 s7, s6, 31
	v_lshl_add_u64 v[12:13], v[12:13], 0, s[12:13]
	s_lshl_b64 s[12:13], s[4:5], 7
	s_mov_b64 s[8:9], 0x264f7700
	s_add_u32 s11, s12, 0x34ff7300
	v_cmp_gt_u32_e32 vcc, 32, v2
	v_lshl_add_u64 v[6:7], v[6:7], 0, s[8:9]
	s_mul_i32 s8, s0, 0x2800
	s_mul_hi_i32 s9, s6, 0x500
	s_mul_i32 s14, s0, 0x1400
	s_mul_hi_i32 s15, s6, 0x280
	s_addc_u32 s22, s13, 0
	s_lshl_b64 s[16:17], s[6:7], 7
	v_mov_b32_e32 v3, 0x358637bd
	s_mov_b32 s23, 0x800000
	s_mov_b32 s24, 0x4080000
	v_lshlrev_b32_e32 v0, 2, v0
	s_mov_b32 s25, 0x5080000
	v_lshlrev_b32_e32 v14, 2, v2
	global_load_dwordx4 v[24:27], v[4:5], off
	v_readlane_b32 s46, v255, 9
	v_readlane_b32 s47, v255, 10
	s_and_b64 s[48:49], vcc, exec
	s_mov_b64 s[50:51], exec
	s_nop 1
	s_add_u32 s12, s82, s11
	s_addc_u32 s13, s83, s22
	v_lshl_add_u64 v[32:33], s[82:83], 0, v[8:9]
	s_and_b32 s26, s1, 0xffe0
	s_cmpk_lt_i32 s4, 0x4000
	s_cselect_b32 s20, s26, 0x10000
	v_lshl_add_u64 v[34:35], s[82:83], 0, v[6:7]
	global_load_dwordx4 v[60:63], v1, s[12:13]
	global_load_dwordx4 v[64:67], v[32:33], off
	v_or_b32_e32 v15, s20, v2
	v_lshlrev_b32_e32 v15, 3, v15
	s_mov_b64 exec, s[48:49]
	global_load_dwordx2 v[68:69], v15, s[46:47]
	global_load_dwordx2 v[70:71], v[34:35], off
	s_mov_b64 exec, s[50:51]
	s_waitcnt vmcnt(0)
.Lmy_kvf_loop:
	v_mov_b32_e32 v72, v60
	v_mov_b32_e32 v73, v61
	v_mov_b32_e32 v74, v62
	v_mov_b32_e32 v75, v63
	v_mov_b32_e32 v76, v64
	v_mov_b32_e32 v77, v65
	v_mov_b32_e32 v78, v66
	v_mov_b32_e32 v79, v67
	v_mov_b32_e32 v80, v68
	v_mov_b32_e32 v81, v69
	v_mov_b32_e32 v82, v70
	v_mov_b32_e32 v83, v71
	s_add_i32 s38, s4, s6
	s_cmpk_lt_i32 s38, 0x4080
	s_cselect_b32 s40, s16, 0
	s_cselect_b32 s41, s17, 0
	s_cselect_b32 s42, s8, 0
	s_cselect_b32 s43, s9, 0
	s_cselect_b32 s44, s2, 0
	s_cselect_b32 s37, s38, s4
	s_add_u32 s12, s82, s11
	s_addc_u32 s13, s83, s22
	s_add_u32 s12, s12, s40
	s_addc_u32 s13, s13, s41
	v_lshl_add_u64 v[32:33], v[8:9], 0, s[42:43]
	v_lshl_add_u64 v[32:33], v[32:33], 0, s[82:83]
	s_add_i32 s26, s1, s44
	s_and_b32 s26, s26, 0xffe0
	s_cmpk_lt_i32 s37, 0x4000
	s_cselect_b32 s20, s26, 0x10000
	v_lshl_add_u64 v[34:35], v[6:7], 0, s[42:43]
	v_lshl_add_u64 v[34:35], v[34:35], 0, s[82:83]
	global_load_dwordx4 v[60:63], v1, s[12:13]
	global_load_dwordx4 v[64:67], v[32:33], off
	v_or_b32_e32 v15, s20, v2
	v_lshlrev_b32_e32 v15, 3, v15
	s_mov_b64 exec, s[48:49]
	global_load_dwordx2 v[68:69], v15, s[46:47]
	global_load_dwordx2 v[70:71], v[34:35], off
	s_mov_b64 exec, s[50:51]
	s_add_i32 s18, s4, 0xffffc000
	s_cmpk_lt_i32 s4, 0x4000
	s_cselect_b32 s12, s24, 0x5480000
	s_cselect_b32 s19, s5, 0
	s_cselect_b32 s18, s4, s18
	s_add_u32 s28, s80, s12
	s_addc_u32 s29, s81, 0
	s_lshl_b64 s[26:27], s[18:19], 10
	s_add_u32 s26, s28, s26
	s_addc_u32 s27, s29, s27
	v_mov_b32_e32 v16, v72
	v_mov_b32_e32 v17, v75
	v_mov_b32_e32 v28, v73
	v_mov_b32_e32 v29, v74
	v_pk_add_f32 v[16:17], v[28:29], v[16:17]
	s_nop 0
	v_add_f32_e32 v15, v16, v17
	v_fmamk_f32 v15, v15, 0x3b800000, v3
	v_mul_f32_e32 v16, 0x4b800000, v15
	v_cmp_gt_f32_e64 s[12:13], s23, v15
	s_nop 1
	v_cndmask_b32_e64 v15, v15, v16, s[12:13]
	v_rsq_f32_e32 v15, v15
	s_nop 0
	v_mul_f32_e32 v16, 0x45800000, v15
	v_cndmask_b32_e64 v16, v15, v16, s[12:13]
	v_pk_mul_f32 v[20:21], v[76:77], v[16:17] op_sel_hi:[1,0]
	v_pk_mul_f32 v[16:17], v[78:79], v[16:17] op_sel_hi:[1,0]
	v_pk_mul_f32 v[18:19], v[26:27], v[16:17]
	v_pk_mul_f32 v[16:17], v[24:25], v[20:21]
	global_store_dwordx4 v0, v[16:19], s[26:27]
	s_nop 1
	v_cvt_pk_bf16_f32 v16, v16, v17
	v_cvt_pk_bf16_f32 v17, v18, v19
	v_lshl_add_u64 v[18:19], s[82:83], 0, v[12:13]
	global_store_dwordx2 v[18:19], v[16:17], off
	s_cmpk_lt_i32 s4, 0x4000
	s_cselect_b32 s20, s25, 0x54a0000
	s_add_u32 s20, s80, s20
	s_addc_u32 s21, s81, 0
	s_lshl_b64 s[18:19], s[18:19], 8
	s_add_u32 s18, s20, s18
	s_addc_u32 s19, s21, s19
	s_mov_b64 exec, s[48:49]
	v_pk_mul_f32 v[20:21], v[82:83], v[80:81]
	v_pk_mul_f32 v[16:17], v[82:83], v[80:81] op_sel:[1,0] op_sel_hi:[0,1]
	v_sub_f32_e32 v15, v20, v21
	v_add_f32_e32 v16, v16, v17
	global_store_dword v14, v15, s[18:19]
	global_store_dword v14, v16, s[18:19] offset:128
	v_cvt_pk_bf16_f32 v15, v15, v16
	v_lshl_add_u64 v[16:17], s[82:83], 0, v[10:11]
	global_store_dword v[16:17], v15, off
	s_mov_b64 exec, s[50:51]
	s_add_u32 s4, s4, s6
	s_addc_u32 s5, s5, s7
	s_add_i32 s1, s1, s2
	s_add_u32 s11, s11, s16
	s_addc_u32 s22, s22, s17
	v_lshl_add_u64 v[6:7], v[6:7], 0, s[8:9]
	v_lshl_add_u64 v[8:9], v[8:9], 0, s[8:9]
	v_lshl_add_u64 v[10:11], v[10:11], 0, s[14:15]
	v_lshl_add_u64 v[12:13], v[12:13], 0, s[14:15]
	s_waitcnt vmcnt(5)
	s_cmpk_lt_i32 s4, 0x4080
	s_cbranch_scc1 .Lmy_kvf_loop
	s_waitcnt vmcnt(0)
	s_branch .LBB0_1973
